# v7 plus MLA up-projection (P4) epilogues: all row partial-sum loads hoisted to epilogue start with counted vmcnt, removing the serialized load-store chain
# speedup vs baseline: 1.0040x; 1.0040x over previous
; #define GAS __attribute__((address_space(1)))
;     __device__ __forceinline__ void operator()(const f32x4 (&acc)[2][2][4][2], const pg8::Unit& u, int wr, int wc, int fr, int fq, const LAS float* scr) const {
;     ...
;             for (int m = 0; m < 4; ++m) { const int row = row0 + ai * 128 + m * 16; const float* rp = part + (size_t)row * NP; float q = 0.f;
; #pragma unroll
;                 for (int j = 0; j < NP / 4; ++j) { const f32x4 t = *(const GAS f32x4*)(rp + 4 * j); q += (t.x + t.y) + (t.z + t.w); }
;                 const float sc = __builtin_amdgcn_rsqf(q * inv_n + EPSN);
; #pragma unroll
;                 for (int bj = 0; bj < 2; ++bj) { const int c0 = u.pn * 256 + bj * 128 + wc * 32, col0 = c0 + 8 * fq;
;                     f32x4 v0 = acc[ai][bj][m][0] * sc, v1 = acc[ai][bj][m][1] * sc;
;                     if (ROPE && ((c0 & ~63) % 192) == 128) { const int j0 = ((c0 & 32) ? 16 : 0) + 4 * fq;
;                         const f32x4 c = *(const GAS f32x4*)(cosM + (size_t)row * 32 + j0), s = *(const GAS f32x4*)(sinM + (size_t)row * 32 + j0);
;                         const f32x4 a = v0 * c - v1 * s, b = v0 * s + v1 * c; v0 = a; v1 = b; }
.LBB0_754:
	v_mov_b32_e32 v138, v195
	s_lshl_b32 s0, s28, 8
	s_add_i32 s0, s0, s41
	v_bfe_u32 v0, v138, 4, 2
	v_and_or_b32 v138, v138, 15, s0
	s_lshl_b32 s0, s2, 8
	s_or_b32 s6, s0, s43
	v_mad_i64_i32 v[148:149], s[0:1], v138, 48, s[14:15]
	global_load_dwordx4 v[162:165], v[148:149], off
	global_load_dwordx4 v[166:169], v[148:149], off offset:16
	global_load_dwordx4 v[170:173], v[148:149], off offset:32
	global_load_dwordx4 v[174:177], v[148:149], off offset:768
	global_load_dwordx4 v[178:181], v[148:149], off offset:784
	global_load_dwordx4 v[182:185], v[148:149], off offset:800
	global_load_dwordx4 v[186:189], v[148:149], off offset:1536
	global_load_dwordx4 v[196:199], v[148:149], off offset:1552
	global_load_dwordx4 v[200:203], v[148:149], off offset:1568
	global_load_dwordx4 v[204:207], v[148:149], off offset:2304
	global_load_dwordx4 v[208:211], v[148:149], off offset:2320
	global_load_dwordx4 v[212:215], v[148:149], off offset:2336
	v_add_u32_e32 v190, 0x80, v138
	v_mad_i64_i32 v[190:191], s[0:1], v190, 48, s[14:15]
	global_load_dwordx4 v[216:219], v[190:191], off
	global_load_dwordx4 v[220:223], v[190:191], off offset:16
	global_load_dwordx4 v[224:227], v[190:191], off offset:32
	global_load_dwordx4 v[228:231], v[190:191], off offset:768
	global_load_dwordx4 v[232:235], v[190:191], off offset:784
	global_load_dwordx4 v[236:239], v[190:191], off offset:800
	v_mov_b32_e32 v241, 0x358637bd
	s_and_b32 s0, s6, 0xffffff40
	s_mul_hi_i32 s1, s0, 0x2aaaaaab
	s_lshr_b32 s2, s1, 31
	s_lshr_b32 s1, s1, 5
	s_add_i32 s1, s1, s2
	v_ashrrev_i32_e32 v139, 31, v138
	s_mulk_i32 s1, 0xc0
	s_sub_i32 s2, s0, s1
	v_lshl_or_b32 v156, v0, 2, s46
	s_cmpk_eq_i32 s2, 0x80
	v_mov_b32_e32 v240, v195
	s_cselect_b64 s[0:1], -1, 0
	s_cmpk_lg_i32 s2, 0x80
	s_waitcnt vmcnt(15)
	v_mov_b64_e32 v[140:141], v[170:171]
	v_mov_b64_e32 v[142:143], v[172:173]
	v_mov_b64_e32 v[144:145], v[166:167]
	v_mov_b64_e32 v[146:147], v[168:169]
	v_mov_b64_e32 v[152:153], v[162:163]
	v_mov_b64_e32 v[154:155], v[164:165]
	v_add_f32_e32 v144, v144, v145
	v_mov_b32_e32 v148, v153
	v_mov_b32_e32 v149, v154
	v_mov_b32_e32 v153, v155
	v_pk_add_f32 v[148:149], v[148:149], v[152:153]
	v_add_f32_e32 v146, v146, v147
	v_pk_add_f32 v[148:149], v[148:149], v[148:149] op_sel:[0,1] op_sel_hi:[1,0]
	v_mov_b32_e32 v145, v142
	v_mov_b32_e32 v149, v140
	v_mov_b32_e32 v140, v1
	v_mov_b32_e32 v147, v143
	v_pk_add_f32 v[140:141], v[148:149], v[140:141]
	v_pk_add_f32 v[142:143], v[144:145], v[146:147]
	v_lshlrev_b64 v[146:147], 5, v[138:139]
	v_pk_add_f32 v[140:141], v[140:141], v[142:143]
	s_nop 0
	v_add_f32_e32 v140, v140, v141
	v_fmamk_f32 v140, v140, 0x3b2aaaab, v241
	v_rsq_f32_e32 v140, v140
	s_nop 0
	v_pk_mul_f32 v[142:143], v[128:129], v[140:141] op_sel_hi:[1,0]
	v_lshlrev_b64 v[128:129], 2, v[146:147]
	v_pk_mul_f32 v[124:125], v[124:125], v[140:141] op_sel_hi:[1,0]
	v_pk_mul_f32 v[122:123], v[122:123], v[140:141] op_sel_hi:[1,0]
	v_pk_mul_f32 v[144:145], v[126:127], v[140:141] op_sel_hi:[1,0]
	v_lshl_add_u64 v[146:147], s[16:17], 0, v[128:129]
	v_lshlrev_b32_e32 v126, 2, v156
	v_lshl_add_u64 v[148:149], s[18:19], 0, v[128:129]
	s_cbranch_scc1 .LBB0_756
	v_mov_b32_e32 v127, v1
	v_lshl_add_u64 v[128:129], v[148:149], 0, v[126:127]
	global_load_dwordx4 v[152:155], v[128:129], off
	v_lshl_add_u64 v[128:129], v[146:147], 0, v[126:127]
	global_load_dwordx4 v[156:159], v[128:129], off
	v_mov_b32_e32 v244, 0x2600
	s_waitcnt vmcnt(1)
	v_pk_mul_f32 v[128:129], v[142:143], v[154:155]
	v_pk_mul_f32 v[160:161], v[144:145], v[152:153]
	v_pk_mul_f32 v[154:155], v[124:125], v[154:155]
	v_pk_mul_f32 v[152:153], v[122:123], v[152:153]
	s_waitcnt vmcnt(0)
	v_pk_fma_f32 v[124:125], v[124:125], v[158:159], v[128:129] neg_lo:[0,0,1] neg_hi:[0,0,1]
	v_pk_fma_f32 v[122:123], v[122:123], v[156:157], v[160:161] neg_lo:[0,0,1] neg_hi:[0,0,1]
	v_pk_fma_f32 v[142:143], v[142:143], v[158:159], v[154:155]
	v_pk_fma_f32 v[144:145], v[144:145], v[156:157], v[152:153]
	s_branch .LBB0_757

; #define GAS __attribute__((address_space(1)))
;     __device__ __forceinline__ void operator()(const f32x4 (&acc)[2][2][4][2], const pg8::Unit& u, int wr, int wc, int fr, int fq, const LAS float* scr) const {
;     ...
;             for (int m = 0; m < 4; ++m) { const int row = row0 + ai * 128 + m * 16; const float* rp = part + (size_t)row * NP; float q = 0.f;
; #pragma unroll
;                 for (int j = 0; j < NP / 4; ++j) { const f32x4 t = *(const GAS f32x4*)(rp + 4 * j); q += (t.x + t.y) + (t.z + t.w); }
;                 const float sc = __builtin_amdgcn_rsqf(q * inv_n + EPSN);
; #pragma unroll
;                 for (int bj = 0; bj < 2; ++bj) { const int c0 = u.pn * 256 + bj * 128 + wc * 32, col0 = c0 + 8 * fq;
;                     f32x4 v0 = acc[ai][bj][m][0] * sc, v1 = acc[ai][bj][m][1] * sc;
;                     if (ROPE && ((c0 & ~63) % 192) == 128) { const int j0 = ((c0 & 32) ? 16 : 0) + 4 * fq;
;                         const f32x4 c = *(const GAS f32x4*)(cosM + (size_t)row * 32 + j0), s = *(const GAS f32x4*)(sinM + (size_t)row * 32 + j0);
;                         const f32x4 a = v0 * c - v1 * s, b = v0 * s + v1 * c; v0 = a; v1 = b; }
.LBB0_759:
	s_ashr_i32 s7, s6, 31
	v_cvt_pk_bf16_f32 v118, v118, v119
	v_cvt_pk_bf16_f32 v119, v120, v121
	v_cvt_pk_bf16_f32 v120, v114, v115
	v_lshl_add_u64 v[114:115], v[0:1], 0, s[6:7]
	v_cvt_pk_bf16_f32 v121, v116, v117
	v_lshl_add_u64 v[116:117], v[114:115], 1, v[122:123]
	global_store_dwordx4 v[116:117], v[118:121], off offset:256
	v_or_b32_e32 v116, 16, v138
	v_mad_i64_i32 v[140:141], s[6:7], v116, 48, s[14:15]
	s_waitcnt vmcnt(14)
	v_mov_b64_e32 v[118:119], v[182:183]
	v_mov_b64_e32 v[120:121], v[184:185]
	v_mov_b64_e32 v[122:123], v[178:179]
	v_mov_b64_e32 v[124:125], v[180:181]
	v_mov_b64_e32 v[140:141], v[174:175]
	v_mov_b64_e32 v[142:143], v[176:177]
	v_ashrrev_i32_e32 v117, 31, v116
	s_andn2_b64 vcc, exec, s[0:1]
	v_add_f32_e32 v122, v122, v123
	v_mov_b32_e32 v144, v141
	v_mov_b32_e32 v145, v142
	v_mov_b32_e32 v141, v143
	v_pk_add_f32 v[140:141], v[144:145], v[140:141]
	v_add_f32_e32 v124, v124, v125
	v_pk_add_f32 v[140:141], v[140:141], v[140:141] op_sel:[0,1] op_sel_hi:[1,0]
	v_mov_b32_e32 v123, v120
	v_mov_b32_e32 v141, v118
	v_mov_b32_e32 v118, v1
	v_mov_b32_e32 v125, v121
	v_pk_add_f32 v[118:119], v[140:141], v[118:119]
	v_pk_add_f32 v[120:121], v[122:123], v[124:125]
	s_nop 0
	v_pk_add_f32 v[118:119], v[118:119], v[120:121]
	v_lshlrev_b64 v[120:121], 5, v[116:117]
	v_add_f32_e32 v0, v118, v119
	v_fmamk_f32 v0, v0, 0x3b2aaaab, v241
	v_rsq_f32_e32 v118, v0
	v_cndmask_b32_e64 v0, 0, 1, s[0:1]
	v_lshlrev_b64 v[122:123], 2, v[120:121]
	v_cmp_ne_u32_e64 s[8:9], 1, v0
	v_pk_mul_f32 v[108:109], v[108:109], v[118:119] op_sel_hi:[1,0]
	v_pk_mul_f32 v[106:107], v[106:107], v[118:119] op_sel_hi:[1,0]
	v_pk_mul_f32 v[112:113], v[112:113], v[118:119] op_sel_hi:[1,0]
	v_pk_mul_f32 v[110:111], v[110:111], v[118:119] op_sel_hi:[1,0]
	v_lshl_add_u64 v[120:121], s[16:17], 0, v[122:123]
	v_lshl_add_u64 v[122:123], s[18:19], 0, v[122:123]
	s_cbranch_vccnz .LBB0_761
	v_mov_b32_e32 v127, v1
	v_lshl_add_u64 v[124:125], v[122:123], 0, v[126:127]
	global_load_dwordx4 v[140:143], v[124:125], off
	v_lshl_add_u64 v[124:125], v[120:121], 0, v[126:127]
	global_load_dwordx4 v[144:147], v[124:125], off
	s_waitcnt vmcnt(1)
	v_pk_mul_f32 v[124:125], v[112:113], v[142:143]
	v_pk_mul_f32 v[148:149], v[110:111], v[140:141]
	v_pk_mul_f32 v[142:143], v[108:109], v[142:143]
	v_pk_mul_f32 v[140:141], v[106:107], v[140:141]
	s_waitcnt vmcnt(0)
	v_pk_fma_f32 v[108:109], v[108:109], v[146:147], v[124:125] neg_lo:[0,0,1] neg_hi:[0,0,1]
	v_pk_fma_f32 v[106:107], v[106:107], v[144:145], v[148:149] neg_lo:[0,0,1] neg_hi:[0,0,1]
	v_pk_fma_f32 v[112:113], v[112:113], v[146:147], v[142:143]
	v_pk_fma_f32 v[110:111], v[110:111], v[144:145], v[140:141]

; #define GAS __attribute__((address_space(1)))
;     __device__ __forceinline__ void operator()(const f32x4 (&acc)[2][2][4][2], const pg8::Unit& u, int wr, int wc, int fr, int fq, const LAS float* scr) const {
;     ...
;             for (int m = 0; m < 4; ++m) { const int row = row0 + ai * 128 + m * 16; const float* rp = part + (size_t)row * NP; float q = 0.f;
; #pragma unroll
;                 for (int j = 0; j < NP / 4; ++j) { const f32x4 t = *(const GAS f32x4*)(rp + 4 * j); q += (t.x + t.y) + (t.z + t.w); }
;                 const float sc = __builtin_amdgcn_rsqf(q * inv_n + EPSN);
; #pragma unroll
;                 for (int bj = 0; bj < 2; ++bj) { const int c0 = u.pn * 256 + bj * 128 + wc * 32, col0 = c0 + 8 * fq;
;                     f32x4 v0 = acc[ai][bj][m][0] * sc, v1 = acc[ai][bj][m][1] * sc;
;                     if (ROPE && ((c0 & ~63) % 192) == 128) { const int j0 = ((c0 & 32) ? 16 : 0) + 4 * fq;
;                         const f32x4 c = *(const GAS f32x4*)(cosM + (size_t)row * 32 + j0), s = *(const GAS f32x4*)(sinM + (size_t)row * 32 + j0);
;                         const f32x4 a = v0 * c - v1 * s, b = v0 * s + v1 * c; v0 = a; v1 = b; }
.LBB0_763:
	v_cvt_pk_bf16_f32 v102, v102, v103
	v_cvt_pk_bf16_f32 v103, v104, v105
	s_nop 0
	v_cvt_pk_bf16_f32 v104, v98, v99
	v_lshl_add_u64 v[98:99], v[114:115], 1, v[106:107]
	v_cvt_pk_bf16_f32 v105, v100, v101
	global_store_dwordx4 v[98:99], v[102:105], off offset:256
	v_or_b32_e32 v98, 32, v138
	v_mad_i64_i32 v[108:109], s[0:1], v98, 48, s[14:15]
	s_waitcnt vmcnt(13)
	v_mov_b64_e32 v[100:101], v[200:201]
	v_mov_b64_e32 v[102:103], v[202:203]
	v_mov_b64_e32 v[104:105], v[196:197]
	v_mov_b64_e32 v[106:107], v[198:199]
	v_mov_b64_e32 v[108:109], v[186:187]
	v_mov_b64_e32 v[110:111], v[188:189]
	v_ashrrev_i32_e32 v99, 31, v98
	s_and_b64 vcc, exec, s[8:9]
	v_add_f32_e32 v104, v104, v105
	v_mov_b32_e32 v112, v109
	v_mov_b32_e32 v113, v110
	v_mov_b32_e32 v109, v111
	v_pk_add_f32 v[108:109], v[112:113], v[108:109]
	v_add_f32_e32 v106, v106, v107
	v_pk_add_f32 v[108:109], v[108:109], v[108:109] op_sel:[0,1] op_sel_hi:[1,0]
	v_mov_b32_e32 v105, v102
	v_mov_b32_e32 v109, v100
	v_mov_b32_e32 v100, v1
	v_mov_b32_e32 v107, v103
	v_pk_add_f32 v[100:101], v[108:109], v[100:101]
	v_pk_add_f32 v[102:103], v[104:105], v[106:107]
	s_nop 0
	v_pk_add_f32 v[100:101], v[100:101], v[102:103]
	v_lshlrev_b64 v[102:103], 5, v[98:99]
	v_add_f32_e32 v0, v100, v101
	v_fmamk_f32 v0, v0, 0x3b2aaaab, v241
	v_rsq_f32_e32 v100, v0
	v_lshlrev_b64 v[104:105], 2, v[102:103]
	v_lshl_add_u64 v[102:103], s[16:17], 0, v[104:105]
	v_lshl_add_u64 v[104:105], s[18:19], 0, v[104:105]
	v_pk_mul_f32 v[92:93], v[92:93], v[100:101] op_sel_hi:[1,0]
	v_pk_mul_f32 v[90:91], v[90:91], v[100:101] op_sel_hi:[1,0]
	v_pk_mul_f32 v[96:97], v[96:97], v[100:101] op_sel_hi:[1,0]
	v_pk_mul_f32 v[94:95], v[94:95], v[100:101] op_sel_hi:[1,0]
	s_cbranch_vccnz .LBB0_765
	v_mov_b32_e32 v127, v1
	v_lshl_add_u64 v[106:107], v[104:105], 0, v[126:127]
	global_load_dwordx4 v[106:109], v[106:107], off
	v_lshl_add_u64 v[110:111], v[102:103], 0, v[126:127]
	global_load_dwordx4 v[110:113], v[110:111], off
	s_waitcnt vmcnt(1)
	v_pk_mul_f32 v[116:117], v[96:97], v[108:109]
	v_pk_mul_f32 v[118:119], v[94:95], v[106:107]
	v_pk_mul_f32 v[108:109], v[92:93], v[108:109]
	v_pk_mul_f32 v[106:107], v[90:91], v[106:107]
	s_waitcnt vmcnt(0)
	v_pk_fma_f32 v[92:93], v[92:93], v[112:113], v[116:117] neg_lo:[0,0,1] neg_hi:[0,0,1]
	v_pk_fma_f32 v[90:91], v[90:91], v[110:111], v[118:119] neg_lo:[0,0,1] neg_hi:[0,0,1]
	v_pk_fma_f32 v[96:97], v[96:97], v[112:113], v[108:109]
	v_pk_fma_f32 v[94:95], v[94:95], v[110:111], v[106:107]

; #define GAS __attribute__((address_space(1)))
;     __device__ __forceinline__ void operator()(const f32x4 (&acc)[2][2][4][2], const pg8::Unit& u, int wr, int wc, int fr, int fq, const LAS float* scr) const {
;     ...
;             for (int m = 0; m < 4; ++m) { const int row = row0 + ai * 128 + m * 16; const float* rp = part + (size_t)row * NP; float q = 0.f;
; #pragma unroll
;                 for (int j = 0; j < NP / 4; ++j) { const f32x4 t = *(const GAS f32x4*)(rp + 4 * j); q += (t.x + t.y) + (t.z + t.w); }
;                 const float sc = __builtin_amdgcn_rsqf(q * inv_n + EPSN);
; #pragma unroll
;                 for (int bj = 0; bj < 2; ++bj) { const int c0 = u.pn * 256 + bj * 128 + wc * 32, col0 = c0 + 8 * fq;
;                     f32x4 v0 = acc[ai][bj][m][0] * sc, v1 = acc[ai][bj][m][1] * sc;
;                     if (ROPE && ((c0 & ~63) % 192) == 128) { const int j0 = ((c0 & 32) ? 16 : 0) + 4 * fq;
;                         const f32x4 c = *(const GAS f32x4*)(cosM + (size_t)row * 32 + j0), s = *(const GAS f32x4*)(sinM + (size_t)row * 32 + j0);
;                         const f32x4 a = v0 * c - v1 * s, b = v0 * s + v1 * c; v0 = a; v1 = b; }
.LBB0_767:
	v_cvt_pk_bf16_f32 v86, v86, v87
	v_cvt_pk_bf16_f32 v87, v88, v89
	s_nop 0
	v_cvt_pk_bf16_f32 v88, v82, v83
	v_lshl_add_u64 v[82:83], v[114:115], 1, v[90:91]
	v_cvt_pk_bf16_f32 v89, v84, v85
	global_store_dwordx4 v[82:83], v[86:89], off offset:256
	v_or_b32_e32 v82, 48, v138
	v_mad_i64_i32 v[92:93], s[0:1], v82, 48, s[14:15]
	s_waitcnt vmcnt(12)
	v_mov_b64_e32 v[84:85], v[212:213]
	v_mov_b64_e32 v[86:87], v[214:215]
	v_mov_b64_e32 v[88:89], v[208:209]
	v_mov_b64_e32 v[90:91], v[210:211]
	v_mov_b64_e32 v[92:93], v[204:205]
	v_mov_b64_e32 v[94:95], v[206:207]
	v_add_u32_e32 v190, 0xa0, v138
	v_mad_i64_i32 v[190:191], s[0:1], v190, 48, s[14:15]
	global_load_dwordx4 v[162:165], v[190:191], off
	global_load_dwordx4 v[166:169], v[190:191], off offset:16
	global_load_dwordx4 v[170:173], v[190:191], off offset:32
	global_load_dwordx4 v[174:177], v[190:191], off offset:768
	global_load_dwordx4 v[178:181], v[190:191], off offset:784
	global_load_dwordx4 v[182:185], v[190:191], off offset:800
	v_ashrrev_i32_e32 v83, 31, v82
	s_and_b64 vcc, exec, s[8:9]
	v_add_f32_e32 v88, v88, v89
	v_mov_b32_e32 v96, v93
	v_mov_b32_e32 v97, v94
	v_mov_b32_e32 v93, v95
	v_pk_add_f32 v[92:93], v[96:97], v[92:93]
	v_add_f32_e32 v90, v90, v91
	v_pk_add_f32 v[92:93], v[92:93], v[92:93] op_sel:[0,1] op_sel_hi:[1,0]
	v_mov_b32_e32 v89, v86
	v_mov_b32_e32 v93, v84
	v_mov_b32_e32 v84, v1
	v_mov_b32_e32 v91, v87
	v_pk_add_f32 v[84:85], v[92:93], v[84:85]
	v_pk_add_f32 v[86:87], v[88:89], v[90:91]
	s_nop 0
	v_pk_add_f32 v[84:85], v[84:85], v[86:87]
	v_lshlrev_b64 v[86:87], 5, v[82:83]
	v_add_f32_e32 v0, v84, v85
	v_fmamk_f32 v0, v0, 0x3b2aaaab, v241
	v_rsq_f32_e32 v84, v0
	v_lshlrev_b64 v[88:89], 2, v[86:87]
	v_lshl_add_u64 v[86:87], s[16:17], 0, v[88:89]
	v_lshl_add_u64 v[88:89], s[18:19], 0, v[88:89]
	v_pk_mul_f32 v[76:77], v[76:77], v[84:85] op_sel_hi:[1,0]
	v_pk_mul_f32 v[74:75], v[74:75], v[84:85] op_sel_hi:[1,0]
	v_pk_mul_f32 v[80:81], v[80:81], v[84:85] op_sel_hi:[1,0]
	v_pk_mul_f32 v[78:79], v[78:79], v[84:85] op_sel_hi:[1,0]
	s_cbranch_vccnz .LBB0_769
	v_mov_b32_e32 v127, v1
	v_lshl_add_u64 v[90:91], v[88:89], 0, v[126:127]
	global_load_dwordx4 v[90:93], v[90:91], off
	v_lshl_add_u64 v[94:95], v[86:87], 0, v[126:127]
	global_load_dwordx4 v[94:97], v[94:95], off
	s_waitcnt vmcnt(1)
	v_pk_mul_f32 v[98:99], v[80:81], v[92:93]
	v_pk_mul_f32 v[100:101], v[78:79], v[90:91]
	v_pk_mul_f32 v[92:93], v[76:77], v[92:93]
	v_pk_mul_f32 v[90:91], v[74:75], v[90:91]
	s_waitcnt vmcnt(0)
	v_pk_fma_f32 v[76:77], v[76:77], v[96:97], v[98:99] neg_lo:[0,0,1] neg_hi:[0,0,1]
	v_pk_fma_f32 v[74:75], v[74:75], v[94:95], v[100:101] neg_lo:[0,0,1] neg_hi:[0,0,1]
	v_pk_fma_f32 v[80:81], v[80:81], v[96:97], v[92:93]
	v_pk_fma_f32 v[78:79], v[78:79], v[94:95], v[90:91]

; #define GAS __attribute__((address_space(1)))
;     __device__ __forceinline__ void operator()(const f32x4 (&acc)[2][2][4][2], const pg8::Unit& u, int wr, int wc, int fr, int fq, const LAS float* scr) const {
;     ...
;             for (int m = 0; m < 4; ++m) { const int row = row0 + ai * 128 + m * 16; const float* rp = part + (size_t)row * NP; float q = 0.f;
; #pragma unroll
;                 for (int j = 0; j < NP / 4; ++j) { const f32x4 t = *(const GAS f32x4*)(rp + 4 * j); q += (t.x + t.y) + (t.z + t.w); }
;                 const float sc = __builtin_amdgcn_rsqf(q * inv_n + EPSN);
; #pragma unroll
;                 for (int bj = 0; bj < 2; ++bj) { const int c0 = u.pn * 256 + bj * 128 + wc * 32, col0 = c0 + 8 * fq;
;                     f32x4 v0 = acc[ai][bj][m][0] * sc, v1 = acc[ai][bj][m][1] * sc;
;                     if (ROPE && ((c0 & ~63) % 192) == 128) { const int j0 = ((c0 & 32) ? 16 : 0) + 4 * fq;
;                         const f32x4 c = *(const GAS f32x4*)(cosM + (size_t)row * 32 + j0), s = *(const GAS f32x4*)(sinM + (size_t)row * 32 + j0);
;                         const f32x4 a = v0 * c - v1 * s, b = v0 * s + v1 * c; v0 = a; v1 = b; }
.LBB0_771:
	v_cvt_pk_bf16_f32 v70, v70, v71
	v_cvt_pk_bf16_f32 v71, v72, v73
	s_nop 0
	v_cvt_pk_bf16_f32 v72, v66, v67
	v_lshl_add_u64 v[66:67], v[114:115], 1, v[74:75]
	v_cvt_pk_bf16_f32 v73, v68, v69
	global_store_dwordx4 v[66:67], v[70:73], off offset:256
	v_add_u32_e32 v66, 0x80, v138
	v_mad_i64_i32 v[76:77], s[0:1], v66, 48, s[14:15]
	s_waitcnt vmcnt(17)
	v_mov_b64_e32 v[68:69], v[224:225]
	v_mov_b64_e32 v[70:71], v[226:227]
	v_mov_b64_e32 v[72:73], v[220:221]
	v_mov_b64_e32 v[74:75], v[222:223]
	v_mov_b64_e32 v[76:77], v[216:217]
	v_mov_b64_e32 v[78:79], v[218:219]
	v_ashrrev_i32_e32 v67, 31, v66
	s_and_b64 vcc, exec, s[8:9]
	v_add_f32_e32 v72, v72, v73
	v_mov_b32_e32 v80, v77
	v_mov_b32_e32 v81, v78
	v_mov_b32_e32 v77, v79
	v_pk_add_f32 v[76:77], v[80:81], v[76:77]
	v_add_f32_e32 v74, v74, v75
	v_pk_add_f32 v[76:77], v[76:77], v[76:77] op_sel:[0,1] op_sel_hi:[1,0]
	v_mov_b32_e32 v73, v70
	v_mov_b32_e32 v77, v68
	v_mov_b32_e32 v68, v1
	v_mov_b32_e32 v75, v71
	v_pk_add_f32 v[68:69], v[76:77], v[68:69]
	v_pk_add_f32 v[70:71], v[72:73], v[74:75]
	s_nop 0
	v_pk_add_f32 v[68:69], v[68:69], v[70:71]
	v_lshlrev_b64 v[70:71], 5, v[66:67]
	v_add_f32_e32 v0, v68, v69
	v_fmamk_f32 v0, v0, 0x3b2aaaab, v241
	v_rsq_f32_e32 v68, v0
	v_lshlrev_b64 v[72:73], 2, v[70:71]
	v_lshl_add_u64 v[70:71], s[16:17], 0, v[72:73]
	v_lshl_add_u64 v[72:73], s[18:19], 0, v[72:73]
	v_pk_mul_f32 v[60:61], v[60:61], v[68:69] op_sel_hi:[1,0]
	v_pk_mul_f32 v[58:59], v[58:59], v[68:69] op_sel_hi:[1,0]
	v_pk_mul_f32 v[64:65], v[64:65], v[68:69] op_sel_hi:[1,0]
	v_pk_mul_f32 v[62:63], v[62:63], v[68:69] op_sel_hi:[1,0]
	s_cbranch_vccnz .LBB0_773
	v_mov_b32_e32 v127, v1
	v_lshl_add_u64 v[74:75], v[72:73], 0, v[126:127]
	global_load_dwordx4 v[74:77], v[74:75], off
	v_lshl_add_u64 v[78:79], v[70:71], 0, v[126:127]
	global_load_dwordx4 v[78:81], v[78:79], off
	s_waitcnt vmcnt(1)
	v_pk_mul_f32 v[82:83], v[64:65], v[76:77]
	v_pk_mul_f32 v[84:85], v[62:63], v[74:75]
	v_pk_mul_f32 v[76:77], v[60:61], v[76:77]
	v_pk_mul_f32 v[74:75], v[58:59], v[74:75]
	s_waitcnt vmcnt(0)
	v_pk_fma_f32 v[60:61], v[60:61], v[80:81], v[82:83] neg_lo:[0,0,1] neg_hi:[0,0,1]
	v_pk_fma_f32 v[58:59], v[58:59], v[78:79], v[84:85] neg_lo:[0,0,1] neg_hi:[0,0,1]
	v_pk_fma_f32 v[64:65], v[64:65], v[80:81], v[76:77]
	v_pk_fma_f32 v[62:63], v[62:63], v[78:79], v[74:75]

; #define GAS __attribute__((address_space(1)))
;     __device__ __forceinline__ void operator()(const f32x4 (&acc)[2][2][4][2], const pg8::Unit& u, int wr, int wc, int fr, int fq, const LAS float* scr) const {
;     ...
;             for (int m = 0; m < 4; ++m) { const int row = row0 + ai * 128 + m * 16; const float* rp = part + (size_t)row * NP; float q = 0.f;
; #pragma unroll
;                 for (int j = 0; j < NP / 4; ++j) { const f32x4 t = *(const GAS f32x4*)(rp + 4 * j); q += (t.x + t.y) + (t.z + t.w); }
;                 const float sc = __builtin_amdgcn_rsqf(q * inv_n + EPSN);
; #pragma unroll
;                 for (int bj = 0; bj < 2; ++bj) { const int c0 = u.pn * 256 + bj * 128 + wc * 32, col0 = c0 + 8 * fq;
;                     f32x4 v0 = acc[ai][bj][m][0] * sc, v1 = acc[ai][bj][m][1] * sc;
;                     if (ROPE && ((c0 & ~63) % 192) == 128) { const int j0 = ((c0 & 32) ? 16 : 0) + 4 * fq;
;                         const f32x4 c = *(const GAS f32x4*)(cosM + (size_t)row * 32 + j0), s = *(const GAS f32x4*)(sinM + (size_t)row * 32 + j0);
;                         const f32x4 a = v0 * c - v1 * s, b = v0 * s + v1 * c; v0 = a; v1 = b; }
.LBB0_775:
	v_cvt_pk_bf16_f32 v54, v54, v55
	v_cvt_pk_bf16_f32 v55, v56, v57
	s_nop 0
	v_cvt_pk_bf16_f32 v56, v50, v51
	v_lshl_add_u64 v[50:51], v[114:115], 1, v[58:59]
	v_cvt_pk_bf16_f32 v57, v52, v53
	global_store_dwordx4 v[50:51], v[54:57], off offset:256
	v_add_u32_e32 v50, 0x90, v138
	v_mad_i64_i32 v[60:61], s[0:1], v50, 48, s[14:15]
	s_waitcnt vmcnt(16)
	v_mov_b64_e32 v[52:53], v[236:237]
	v_mov_b64_e32 v[54:55], v[238:239]
	v_mov_b64_e32 v[56:57], v[232:233]
	v_mov_b64_e32 v[58:59], v[234:235]
	v_mov_b64_e32 v[60:61], v[228:229]
	v_mov_b64_e32 v[62:63], v[230:231]
	v_ashrrev_i32_e32 v51, 31, v50
	s_and_b64 vcc, exec, s[8:9]
	v_add_f32_e32 v56, v56, v57
	v_mov_b32_e32 v64, v61
	v_mov_b32_e32 v65, v62
	v_mov_b32_e32 v61, v63
	v_pk_add_f32 v[60:61], v[64:65], v[60:61]
	v_add_f32_e32 v58, v58, v59
	v_pk_add_f32 v[60:61], v[60:61], v[60:61] op_sel:[0,1] op_sel_hi:[1,0]
	v_mov_b32_e32 v57, v54
	v_mov_b32_e32 v61, v52
	v_mov_b32_e32 v52, v1
	v_mov_b32_e32 v59, v55
	v_pk_add_f32 v[52:53], v[60:61], v[52:53]
	v_pk_add_f32 v[54:55], v[56:57], v[58:59]
	s_nop 0
	v_pk_add_f32 v[52:53], v[52:53], v[54:55]
	v_lshlrev_b64 v[54:55], 5, v[50:51]
	v_add_f32_e32 v0, v52, v53
	v_fmamk_f32 v0, v0, 0x3b2aaaab, v241
	v_rsq_f32_e32 v52, v0
	v_lshlrev_b64 v[56:57], 2, v[54:55]
	v_lshl_add_u64 v[54:55], s[16:17], 0, v[56:57]
	v_lshl_add_u64 v[56:57], s[18:19], 0, v[56:57]
	v_pk_mul_f32 v[44:45], v[44:45], v[52:53] op_sel_hi:[1,0]
	v_pk_mul_f32 v[42:43], v[42:43], v[52:53] op_sel_hi:[1,0]
	v_pk_mul_f32 v[48:49], v[48:49], v[52:53] op_sel_hi:[1,0]
	v_pk_mul_f32 v[46:47], v[46:47], v[52:53] op_sel_hi:[1,0]
	s_cbranch_vccnz .LBB0_777
	v_mov_b32_e32 v127, v1
	v_lshl_add_u64 v[58:59], v[56:57], 0, v[126:127]
	global_load_dwordx4 v[58:61], v[58:59], off
	v_lshl_add_u64 v[62:63], v[54:55], 0, v[126:127]
	global_load_dwordx4 v[62:65], v[62:63], off
	s_waitcnt vmcnt(1)
	v_pk_mul_f32 v[66:67], v[48:49], v[60:61]
	v_pk_mul_f32 v[68:69], v[46:47], v[58:59]
	v_pk_mul_f32 v[60:61], v[44:45], v[60:61]
	v_pk_mul_f32 v[58:59], v[42:43], v[58:59]
	s_waitcnt vmcnt(0)
	v_pk_fma_f32 v[44:45], v[44:45], v[64:65], v[66:67] neg_lo:[0,0,1] neg_hi:[0,0,1]
	v_pk_fma_f32 v[42:43], v[42:43], v[62:63], v[68:69] neg_lo:[0,0,1] neg_hi:[0,0,1]
	v_pk_fma_f32 v[48:49], v[48:49], v[64:65], v[60:61]
	v_pk_fma_f32 v[46:47], v[46:47], v[62:63], v[58:59]

; #define GAS __attribute__((address_space(1)))
;     __device__ __forceinline__ void operator()(const f32x4 (&acc)[2][2][4][2], const pg8::Unit& u, int wr, int wc, int fr, int fq, const LAS float* scr) const {
;     ...
;             for (int m = 0; m < 4; ++m) { const int row = row0 + ai * 128 + m * 16; const float* rp = part + (size_t)row * NP; float q = 0.f;
; #pragma unroll
;                 for (int j = 0; j < NP / 4; ++j) { const f32x4 t = *(const GAS f32x4*)(rp + 4 * j); q += (t.x + t.y) + (t.z + t.w); }
;                 const float sc = __builtin_amdgcn_rsqf(q * inv_n + EPSN);
; #pragma unroll
;                 for (int bj = 0; bj < 2; ++bj) { const int c0 = u.pn * 256 + bj * 128 + wc * 32, col0 = c0 + 8 * fq;
;                     f32x4 v0 = acc[ai][bj][m][0] * sc, v1 = acc[ai][bj][m][1] * sc;
;                     if (ROPE && ((c0 & ~63) % 192) == 128) { const int j0 = ((c0 & 32) ? 16 : 0) + 4 * fq;
;                         const f32x4 c = *(const GAS f32x4*)(cosM + (size_t)row * 32 + j0), s = *(const GAS f32x4*)(sinM + (size_t)row * 32 + j0);
;                         const f32x4 a = v0 * c - v1 * s, b = v0 * s + v1 * c; v0 = a; v1 = b; }
.LBB0_779:
	v_cvt_pk_bf16_f32 v38, v38, v39
	v_cvt_pk_bf16_f32 v39, v40, v41
	s_nop 0
	v_cvt_pk_bf16_f32 v40, v34, v35
	v_lshl_add_u64 v[34:35], v[114:115], 1, v[42:43]
	v_cvt_pk_bf16_f32 v41, v36, v37
	global_store_dwordx4 v[34:35], v[38:41], off offset:256
	v_add_u32_e32 v34, 0xa0, v138
	v_mad_i64_i32 v[44:45], s[0:1], v34, 48, s[14:15]
	s_waitcnt vmcnt(9)
	v_mov_b64_e32 v[36:37], v[170:171]
	v_mov_b64_e32 v[38:39], v[172:173]
	v_mov_b64_e32 v[40:41], v[166:167]
	v_mov_b64_e32 v[42:43], v[168:169]
	v_mov_b64_e32 v[44:45], v[162:163]
	v_mov_b64_e32 v[46:47], v[164:165]
	v_ashrrev_i32_e32 v35, 31, v34
	s_and_b64 vcc, exec, s[8:9]
	v_add_f32_e32 v40, v40, v41
	v_mov_b32_e32 v48, v45
	v_mov_b32_e32 v49, v46
	v_mov_b32_e32 v45, v47
	v_pk_add_f32 v[44:45], v[48:49], v[44:45]
	v_add_f32_e32 v42, v42, v43
	v_pk_add_f32 v[44:45], v[44:45], v[44:45] op_sel:[0,1] op_sel_hi:[1,0]
	v_mov_b32_e32 v41, v38
	v_mov_b32_e32 v45, v36
	v_mov_b32_e32 v36, v1
	v_mov_b32_e32 v43, v39
	v_pk_add_f32 v[36:37], v[44:45], v[36:37]
	v_pk_add_f32 v[38:39], v[40:41], v[42:43]
	s_nop 0
	v_pk_add_f32 v[36:37], v[36:37], v[38:39]
	v_lshlrev_b64 v[38:39], 5, v[34:35]
	v_add_f32_e32 v0, v36, v37
	v_fmamk_f32 v0, v0, 0x3b2aaaab, v241
	v_rsq_f32_e32 v36, v0
	v_lshlrev_b64 v[40:41], 2, v[38:39]
	v_lshl_add_u64 v[38:39], s[16:17], 0, v[40:41]
	v_lshl_add_u64 v[40:41], s[18:19], 0, v[40:41]
	v_pk_mul_f32 v[28:29], v[28:29], v[36:37] op_sel_hi:[1,0]
	v_pk_mul_f32 v[26:27], v[26:27], v[36:37] op_sel_hi:[1,0]
	v_pk_mul_f32 v[32:33], v[32:33], v[36:37] op_sel_hi:[1,0]
	v_pk_mul_f32 v[30:31], v[30:31], v[36:37] op_sel_hi:[1,0]
	s_cbranch_vccnz .LBB0_781
	v_mov_b32_e32 v127, v1
	v_lshl_add_u64 v[42:43], v[40:41], 0, v[126:127]
	global_load_dwordx4 v[42:45], v[42:43], off
	v_lshl_add_u64 v[46:47], v[38:39], 0, v[126:127]
	global_load_dwordx4 v[46:49], v[46:47], off
	s_waitcnt vmcnt(1)
	v_pk_mul_f32 v[50:51], v[32:33], v[44:45]
	v_pk_mul_f32 v[52:53], v[30:31], v[42:43]
	v_pk_mul_f32 v[44:45], v[28:29], v[44:45]
	v_pk_mul_f32 v[42:43], v[26:27], v[42:43]
	s_waitcnt vmcnt(0)
	v_pk_fma_f32 v[28:29], v[28:29], v[48:49], v[50:51] neg_lo:[0,0,1] neg_hi:[0,0,1]
	v_pk_fma_f32 v[26:27], v[26:27], v[46:47], v[52:53] neg_lo:[0,0,1] neg_hi:[0,0,1]
	v_pk_fma_f32 v[32:33], v[32:33], v[48:49], v[44:45]
	v_pk_fma_f32 v[30:31], v[30:31], v[46:47], v[42:43]

; #define GAS __attribute__((address_space(1)))
;     __device__ __forceinline__ void operator()(const f32x4 (&acc)[2][2][4][2], const pg8::Unit& u, int wr, int wc, int fr, int fq, const LAS float* scr) const {
;     ...
;             for (int m = 0; m < 4; ++m) { const int row = row0 + ai * 128 + m * 16; const float* rp = part + (size_t)row * NP; float q = 0.f;
; #pragma unroll
;                 for (int j = 0; j < NP / 4; ++j) { const f32x4 t = *(const GAS f32x4*)(rp + 4 * j); q += (t.x + t.y) + (t.z + t.w); }
;                 const float sc = __builtin_amdgcn_rsqf(q * inv_n + EPSN);
; #pragma unroll
;                 for (int bj = 0; bj < 2; ++bj) { const int c0 = u.pn * 256 + bj * 128 + wc * 32, col0 = c0 + 8 * fq;
;                     f32x4 v0 = acc[ai][bj][m][0] * sc, v1 = acc[ai][bj][m][1] * sc;
;                     if (ROPE && ((c0 & ~63) % 192) == 128) { const int j0 = ((c0 & 32) ? 16 : 0) + 4 * fq;
;                         const f32x4 c = *(const GAS f32x4*)(cosM + (size_t)row * 32 + j0), s = *(const GAS f32x4*)(sinM + (size_t)row * 32 + j0);
;                         const f32x4 a = v0 * c - v1 * s, b = v0 * s + v1 * c; v0 = a; v1 = b; }
.LBB0_783:
	v_cvt_pk_bf16_f32 v22, v22, v23
	v_cvt_pk_bf16_f32 v23, v24, v25
	s_nop 0
	v_cvt_pk_bf16_f32 v24, v18, v19
	v_lshl_add_u64 v[18:19], v[114:115], 1, v[26:27]
	v_cvt_pk_bf16_f32 v25, v20, v21
	global_store_dwordx4 v[18:19], v[22:25], off offset:256
	v_add_u32_e32 v18, 0xb0, v138
	v_mad_i64_i32 v[28:29], s[0:1], v18, 48, s[14:15]
	s_waitcnt vmcnt(8)
	v_mov_b64_e32 v[20:21], v[174:175]
	v_mov_b64_e32 v[22:23], v[176:177]
	v_mov_b64_e32 v[24:25], v[178:179]
	v_mov_b64_e32 v[26:27], v[180:181]
	v_mov_b64_e32 v[28:29], v[182:183]
	v_mov_b64_e32 v[30:31], v[184:185]
	v_ashrrev_i32_e32 v19, 31, v18
	s_and_b64 vcc, exec, s[8:9]
	v_mov_b32_e32 v32, v21
	v_mov_b32_e32 v33, v22
	v_mov_b32_e32 v21, v23
	v_pk_add_f32 v[20:21], v[32:33], v[20:21]
	v_add_f32_e32 v22, v24, v25
	v_pk_add_f32 v[20:21], v[20:21], v[20:21] op_sel:[0,1] op_sel_hi:[1,0]
	v_add_f32_e32 v24, v26, v27
	v_mov_b32_e32 v23, v30
	v_mov_b32_e32 v25, v31
	v_mov_b32_e32 v21, v28
	v_mov_b32_e32 v28, v1
	v_pk_add_f32 v[22:23], v[22:23], v[24:25]
	v_pk_add_f32 v[20:21], v[20:21], v[28:29]
	s_nop 0
	v_pk_add_f32 v[20:21], v[20:21], v[22:23]
	v_lshlrev_b64 v[22:23], 5, v[18:19]
	v_add_f32_e32 v0, v20, v21
	v_fmamk_f32 v0, v0, 0x3b2aaaab, v241
	v_rsq_f32_e32 v20, v0
	v_lshlrev_b64 v[26:27], 2, v[22:23]
	v_lshl_add_u64 v[22:23], s[16:17], 0, v[26:27]
	v_pk_mul_f32 v[12:13], v[12:13], v[20:21] op_sel_hi:[1,0]
	v_pk_mul_f32 v[10:11], v[10:11], v[20:21] op_sel_hi:[1,0]
	v_pk_mul_f32 v[16:17], v[16:17], v[20:21] op_sel_hi:[1,0]
	v_pk_mul_f32 v[24:25], v[14:15], v[20:21] op_sel_hi:[1,0]
	v_lshl_add_u64 v[14:15], s[18:19], 0, v[26:27]
	s_cbranch_vccnz .LBB0_785
	v_mov_b32_e32 v127, v1
	v_lshl_add_u64 v[26:27], v[14:15], 0, v[126:127]
	global_load_dwordx4 v[26:29], v[26:27], off
	v_lshl_add_u64 v[30:31], v[22:23], 0, v[126:127]
	global_load_dwordx4 v[30:33], v[30:31], off
	s_waitcnt vmcnt(1)
	v_pk_mul_f32 v[34:35], v[16:17], v[28:29]
	v_pk_mul_f32 v[36:37], v[24:25], v[26:27]
	v_pk_mul_f32 v[28:29], v[12:13], v[28:29]
	v_pk_mul_f32 v[26:27], v[10:11], v[26:27]
	s_waitcnt vmcnt(0)
	v_pk_fma_f32 v[12:13], v[12:13], v[32:33], v[34:35] neg_lo:[0,0,1] neg_hi:[0,0,1]
	v_pk_fma_f32 v[10:11], v[10:11], v[30:31], v[36:37] neg_lo:[0,0,1] neg_hi:[0,0,1]
	v_pk_fma_f32 v[16:17], v[16:17], v[32:33], v[28:29]
	v_pk_fma_f32 v[24:25], v[24:25], v[30:31], v[26:27]

; #define GAS __attribute__((address_space(1)))
; __device__ __forceinline__ unsigned cvtpk(float lo, float hi) { unsigned r; asm volatile("v_cvt_pk_bf16_f32 %0, %1, %2" : "=v"(r) : "v"(lo), "v"(hi)); return r; }
;     __device__ __forceinline__ void operator()(const f32x4 (&acc)[2][2][4][2], const pg8::Unit& u, int wr, int wc, int fr, int fq, const LAS float* scr) const {
;     ...
;             for (int m = 0; m < 4; ++m) { const int row = row0 + ai * 128 + m * 16; const float* rp = part + (size_t)row * NP; float q = 0.f;
; #pragma unroll
;                 for (int j = 0; j < NP / 4; ++j) { const f32x4 t = *(const GAS f32x4*)(rp + 4 * j); q += (t.x + t.y) + (t.z + t.w); }
;                 const float sc = __builtin_amdgcn_rsqf(q * inv_n + EPSN);
; #pragma unroll
;                 for (int bj = 0; bj < 2; ++bj) { const int c0 = u.pn * 256 + bj * 128 + wc * 32, col0 = c0 + 8 * fq;
;                     f32x4 v0 = acc[ai][bj][m][0] * sc, v1 = acc[ai][bj][m][1] * sc;
;                     if (ROPE && ((c0 & ~63) % 192) == 128) { const int j0 = ((c0 & 32) ? 16 : 0) + 4 * fq;
;                         const f32x4 c = *(const GAS f32x4*)(cosM + (size_t)row * 32 + j0), s = *(const GAS f32x4*)(sinM + (size_t)row * 32 + j0);
;                         const f32x4 a = v0 * c - v1 * s, b = v0 * s + v1 * c; v0 = a; v1 = b; }
;                     u32x4 w; w.x = cvtpk(v0[0], v0[1]); w.y = cvtpk(v0[2], v0[3]); w.z = cvtpk(v1[0], v1[1]); w.w = cvtpk(v1[2], v1[3]);
;                     *(GAS u32x4*)(O + (size_t)row * ldc + col0) = w; }
.LBB0_807:
	v_mov_b32_e32 v137, v240
	s_lshl_b32 s0, s43, 8
	s_add_i32 s0, s0, s37
	v_and_or_b32 v136, v137, 15, s0
	s_lshl_b32 s0, s2, 8
	v_lshrrev_b32_e32 v137, 1, v137
	v_and_or_b32 v137, v137, 24, s0
	v_or_b32_e32 v148, s38, v137
	v_ashrrev_i32_e32 v137, 31, v136
	v_lshlrev_b64 v[140:141], 5, v[136:137]
	v_lshl_add_u64 v[144:145], s[12:13], 0, v[140:141]
	v_mov_b64_e32 v[220:221], v[144:145]
	v_add_co_u32_e32 v222, vcc, 0x1000, v220
	s_nop 1
	v_addc_co_u32_e32 v223, vcc, 0, v221, vcc
	global_load_dwordx4 v[152:155], v[220:221], off
	global_load_dwordx4 v[156:159], v[220:221], off offset:16
	global_load_dwordx4 v[160:163], v[220:221], off offset:512
	global_load_dwordx4 v[164:167], v[220:221], off offset:528
	global_load_dwordx4 v[168:171], v[220:221], off offset:1024
	global_load_dwordx4 v[172:175], v[220:221], off offset:1040
	global_load_dwordx4 v[176:179], v[220:221], off offset:1536
	global_load_dwordx4 v[180:183], v[220:221], off offset:1552
	global_load_dwordx4 v[184:187], v[222:223], off
	global_load_dwordx4 v[188:191], v[222:223], off offset:16
	global_load_dwordx4 v[196:199], v[222:223], off offset:512
	global_load_dwordx4 v[200:203], v[222:223], off offset:528
	global_load_dwordx4 v[204:207], v[222:223], off offset:1024
	global_load_dwordx4 v[208:211], v[222:223], off offset:1040
	global_load_dwordx4 v[212:215], v[222:223], off offset:1536
	global_load_dwordx4 v[216:219], v[222:223], off offset:1552
	v_ashrrev_i32_e32 v149, 31, v148
	s_mov_b64 s[0:1], -1
	s_and_b64 vcc, exec, s[6:7]
	s_waitcnt vmcnt(14)
	v_mov_b64_e32 v[140:141], v[152:153]
	v_mov_b64_e32 v[142:143], v[154:155]
	v_mov_b64_e32 v[144:145], v[156:157]
	v_mov_b64_e32 v[146:147], v[158:159]
	v_mov_b32_e32 v150, v140
	v_mov_b32_e32 v151, v144
	v_mov_b32_e32 v144, v141
	v_pk_add_f32 v[140:141], v[150:151], v[144:145]
	v_mov_b32_e32 v144, v142
	v_mov_b32_e32 v145, v146
	v_mov_b32_e32 v146, v143
	v_pk_add_f32 v[142:143], v[144:145], v[146:147]
	s_nop 0
	v_pk_add_f32 v[140:141], v[140:141], v[142:143]
	s_nop 0
	v_add_f32_e32 v140, 0, v140
	v_add_f32_e32 v140, v140, v141
	v_fmamk_f32 v140, v140, 0x3b800000, v241
	v_rsq_f32_e32 v140, v140
	s_nop 0
	v_pk_mul_f32 v[114:115], v[114:115], v[140:141] op_sel_hi:[1,0]
	v_pk_mul_f32 v[142:143], v[116:117], v[140:141] op_sel_hi:[1,0]
	v_pk_mul_f32 v[120:121], v[120:121], v[140:141] op_sel_hi:[1,0]
	v_pk_mul_f32 v[118:119], v[118:119], v[140:141] op_sel_hi:[1,0]
	v_cvt_pk_bf16_f32 v116, v114, v115
	v_lshlrev_b64 v[114:115], 11, v[136:137]
	v_cvt_pk_bf16_f32 v117, v142, v143
	v_cvt_pk_bf16_f32 v118, v118, v119
	v_cvt_pk_bf16_f32 v119, v120, v121
	v_lshl_add_u64 v[120:121], s[10:11], 0, v[114:115]
	v_lshlrev_b64 v[114:115], 1, v[148:149]
	v_lshl_add_u64 v[120:121], v[120:121], 0, v[114:115]
	global_store_dwordx4 v[120:121], v[116:119], off
	s_nop 1
	v_pk_mul_f32 v[118:119], v[124:125], v[140:141] op_sel_hi:[1,0]
	v_pk_mul_f32 v[116:117], v[122:123], v[140:141] op_sel_hi:[1,0]
	v_pk_mul_f32 v[124:125], v[126:127], v[140:141] op_sel_hi:[1,0]
	v_cvt_pk_bf16_f32 v116, v116, v117
	v_cvt_pk_bf16_f32 v117, v118, v119
	v_pk_mul_f32 v[122:123], v[128:129], v[140:141] op_sel_hi:[1,0]
	v_cvt_pk_bf16_f32 v118, v124, v125
	v_or_b32_e32 v124, 16, v136
	v_ashrrev_i32_e32 v125, 31, v124
	v_cvt_pk_bf16_f32 v119, v122, v123
	global_store_dwordx4 v[120:121], v[116:119], off offset:256
	s_nop 1
	v_lshlrev_b64 v[116:117], 5, v[124:125]
	v_lshl_add_u64 v[120:121], s[12:13], 0, v[116:117]
	s_waitcnt vmcnt(14)
	v_mov_b64_e32 v[116:117], v[160:161]
	v_mov_b64_e32 v[118:119], v[162:163]
	v_mov_b64_e32 v[120:121], v[164:165]
	v_mov_b64_e32 v[122:123], v[166:167]
	v_mov_b32_e32 v126, v116
	v_mov_b32_e32 v127, v120
	v_mov_b32_e32 v120, v117
	v_pk_add_f32 v[116:117], v[126:127], v[120:121]
	v_mov_b32_e32 v120, v118
	v_mov_b32_e32 v121, v122
	v_mov_b32_e32 v122, v119
	v_pk_add_f32 v[118:119], v[120:121], v[122:123]
	s_nop 0
	v_pk_add_f32 v[116:117], v[116:117], v[118:119]
	s_nop 0
	v_add_f32_e32 v116, 0, v116
	v_add_f32_e32 v116, v116, v117
	v_fmamk_f32 v116, v116, 0x3b800000, v241
	v_rsq_f32_e32 v116, v116
	s_nop 0
	v_pk_mul_f32 v[100:101], v[100:101], v[116:117] op_sel_hi:[1,0]
	v_pk_mul_f32 v[98:99], v[98:99], v[116:117] op_sel_hi:[1,0]
	v_pk_mul_f32 v[102:103], v[102:103], v[116:117] op_sel_hi:[1,0]
	v_cvt_pk_bf16_f32 v98, v98, v99
	v_cvt_pk_bf16_f32 v99, v100, v101
	v_pk_mul_f32 v[104:105], v[104:105], v[116:117] op_sel_hi:[1,0]
	v_cvt_pk_bf16_f32 v100, v102, v103
	v_lshlrev_b64 v[102:103], 11, v[124:125]
	v_lshl_add_u64 v[102:103], s[10:11], 0, v[102:103]
	v_cvt_pk_bf16_f32 v101, v104, v105
	v_lshl_add_u64 v[102:103], v[102:103], 0, v[114:115]
	global_store_dwordx4 v[102:103], v[98:101], off
	v_pk_mul_f32 v[104:105], v[112:113], v[116:117] op_sel_hi:[1,0]
	s_nop 0
	v_pk_mul_f32 v[100:101], v[108:109], v[116:117] op_sel_hi:[1,0]
	v_pk_mul_f32 v[98:99], v[106:107], v[116:117] op_sel_hi:[1,0]
	v_pk_mul_f32 v[106:107], v[110:111], v[116:117] op_sel_hi:[1,0]
	v_cvt_pk_bf16_f32 v98, v98, v99
	v_cvt_pk_bf16_f32 v99, v100, v101
	s_nop 0
	v_cvt_pk_bf16_f32 v100, v106, v107
	v_or_b32_e32 v106, 32, v136
	v_ashrrev_i32_e32 v107, 31, v106
	v_cvt_pk_bf16_f32 v101, v104, v105
	global_store_dwordx4 v[102:103], v[98:101], off offset:256
	s_nop 1
	v_lshlrev_b64 v[98:99], 5, v[106:107]
	v_lshl_add_u64 v[102:103], s[12:13], 0, v[98:99]
	s_waitcnt vmcnt(14)
; #define GAS __attribute__((address_space(1)))
; __device__ __forceinline__ unsigned cvtpk(float lo, float hi) { unsigned r; asm volatile("v_cvt_pk_bf16_f32 %0, %1, %2" : "=v"(r) : "v"(lo), "v"(hi)); return r; }
;     __device__ __forceinline__ void operator()(const f32x4 (&acc)[2][2][4][2], const pg8::Unit& u, int wr, int wc, int fr, int fq, const LAS float* scr) const {
;     ...
;             for (int m = 0; m < 4; ++m) { const int row = row0 + ai * 128 + m * 16; const float* rp = part + (size_t)row * NP; float q = 0.f;
; #pragma unroll
;                 for (int j = 0; j < NP / 4; ++j) { const f32x4 t = *(const GAS f32x4*)(rp + 4 * j); q += (t.x + t.y) + (t.z + t.w); }
;                 const float sc = __builtin_amdgcn_rsqf(q * inv_n + EPSN);
; #pragma unroll
;                 for (int bj = 0; bj < 2; ++bj) { const int c0 = u.pn * 256 + bj * 128 + wc * 32, col0 = c0 + 8 * fq;
;                     f32x4 v0 = acc[ai][bj][m][0] * sc, v1 = acc[ai][bj][m][1] * sc;
;                     if (ROPE && ((c0 & ~63) % 192) == 128) { const int j0 = ((c0 & 32) ? 16 : 0) + 4 * fq;
;                         const f32x4 c = *(const GAS f32x4*)(cosM + (size_t)row * 32 + j0), s = *(const GAS f32x4*)(sinM + (size_t)row * 32 + j0);
;                         const f32x4 a = v0 * c - v1 * s, b = v0 * s + v1 * c; v0 = a; v1 = b; }
;                     u32x4 w; w.x = cvtpk(v0[0], v0[1]); w.y = cvtpk(v0[2], v0[3]); w.z = cvtpk(v1[0], v1[1]); w.w = cvtpk(v1[2], v1[3]);
;                     *(GAS u32x4*)(O + (size_t)row * ldc + col0) = w; }
	v_mov_b64_e32 v[98:99], v[168:169]
	v_mov_b64_e32 v[100:101], v[170:171]
	v_mov_b64_e32 v[102:103], v[172:173]
	v_mov_b64_e32 v[104:105], v[174:175]
	v_mov_b32_e32 v108, v98
	v_mov_b32_e32 v109, v102
	v_mov_b32_e32 v102, v99
	v_pk_add_f32 v[98:99], v[108:109], v[102:103]
	v_mov_b32_e32 v102, v100
	v_mov_b32_e32 v103, v104
	v_mov_b32_e32 v104, v101
	v_pk_add_f32 v[100:101], v[102:103], v[104:105]
	s_nop 0
	v_pk_add_f32 v[98:99], v[98:99], v[100:101]
	s_nop 0
	v_add_f32_e32 v98, 0, v98
	v_add_f32_e32 v98, v98, v99
	v_fmamk_f32 v98, v98, 0x3b800000, v241
	v_rsq_f32_e32 v98, v98
	s_nop 0
	v_pk_mul_f32 v[84:85], v[84:85], v[98:99] op_sel_hi:[1,0]
	v_pk_mul_f32 v[82:83], v[82:83], v[98:99] op_sel_hi:[1,0]
	v_pk_mul_f32 v[86:87], v[86:87], v[98:99] op_sel_hi:[1,0]
	v_cvt_pk_bf16_f32 v82, v82, v83
	v_cvt_pk_bf16_f32 v83, v84, v85
	v_pk_mul_f32 v[88:89], v[88:89], v[98:99] op_sel_hi:[1,0]
	v_cvt_pk_bf16_f32 v84, v86, v87
	v_lshlrev_b64 v[86:87], 11, v[106:107]
	v_lshl_add_u64 v[86:87], s[10:11], 0, v[86:87]
	v_cvt_pk_bf16_f32 v85, v88, v89
	v_lshl_add_u64 v[86:87], v[86:87], 0, v[114:115]
	global_store_dwordx4 v[86:87], v[82:85], off
	v_pk_mul_f32 v[88:89], v[96:97], v[98:99] op_sel_hi:[1,0]
	s_nop 0
	v_pk_mul_f32 v[84:85], v[92:93], v[98:99] op_sel_hi:[1,0]
	v_pk_mul_f32 v[82:83], v[90:91], v[98:99] op_sel_hi:[1,0]
	v_pk_mul_f32 v[90:91], v[94:95], v[98:99] op_sel_hi:[1,0]
	v_cvt_pk_bf16_f32 v82, v82, v83
	v_cvt_pk_bf16_f32 v83, v84, v85
	s_nop 0
	v_cvt_pk_bf16_f32 v84, v90, v91
	v_or_b32_e32 v90, 48, v136
	v_ashrrev_i32_e32 v91, 31, v90
	v_cvt_pk_bf16_f32 v85, v88, v89
	global_store_dwordx4 v[86:87], v[82:85], off offset:256
	s_nop 1
	v_lshlrev_b64 v[82:83], 5, v[90:91]
	v_lshl_add_u64 v[86:87], s[12:13], 0, v[82:83]
	s_waitcnt vmcnt(14)
	v_mov_b64_e32 v[82:83], v[176:177]
	v_mov_b64_e32 v[84:85], v[178:179]
	v_mov_b64_e32 v[86:87], v[180:181]
	v_mov_b64_e32 v[88:89], v[182:183]
	v_mov_b32_e32 v92, v82
	v_mov_b32_e32 v93, v86
	v_mov_b32_e32 v86, v83
	v_pk_add_f32 v[82:83], v[92:93], v[86:87]
	v_mov_b32_e32 v86, v84
	v_mov_b32_e32 v87, v88
	v_mov_b32_e32 v88, v85
	v_pk_add_f32 v[84:85], v[86:87], v[88:89]
	s_nop 0
	v_pk_add_f32 v[82:83], v[82:83], v[84:85]
	s_nop 0
	v_add_f32_e32 v82, 0, v82
	v_add_f32_e32 v82, v82, v83
	v_fmamk_f32 v82, v82, 0x3b800000, v241
	v_rsq_f32_e32 v82, v82
	s_nop 0
	v_pk_mul_f32 v[68:69], v[68:69], v[82:83] op_sel_hi:[1,0]
	v_pk_mul_f32 v[66:67], v[66:67], v[82:83] op_sel_hi:[1,0]
	v_pk_mul_f32 v[70:71], v[70:71], v[82:83] op_sel_hi:[1,0]
	v_cvt_pk_bf16_f32 v66, v66, v67
	v_cvt_pk_bf16_f32 v67, v68, v69
	v_pk_mul_f32 v[72:73], v[72:73], v[82:83] op_sel_hi:[1,0]
	v_cvt_pk_bf16_f32 v68, v70, v71
	v_lshlrev_b64 v[70:71], 11, v[90:91]
	v_lshl_add_u64 v[70:71], s[10:11], 0, v[70:71]
	v_cvt_pk_bf16_f32 v69, v72, v73
	v_lshl_add_u64 v[70:71], v[70:71], 0, v[114:115]
	global_store_dwordx4 v[70:71], v[66:69], off
	v_pk_mul_f32 v[72:73], v[80:81], v[82:83] op_sel_hi:[1,0]
	s_nop 0
	v_pk_mul_f32 v[68:69], v[76:77], v[82:83] op_sel_hi:[1,0]
	v_pk_mul_f32 v[66:67], v[74:75], v[82:83] op_sel_hi:[1,0]
	v_pk_mul_f32 v[74:75], v[78:79], v[82:83] op_sel_hi:[1,0]
	v_cvt_pk_bf16_f32 v66, v66, v67
	v_cvt_pk_bf16_f32 v67, v68, v69
	s_nop 0
	v_cvt_pk_bf16_f32 v68, v74, v75
	v_add_u32_e32 v74, 0x80, v136
	v_ashrrev_i32_e32 v75, 31, v74
	v_cvt_pk_bf16_f32 v69, v72, v73
	global_store_dwordx4 v[70:71], v[66:69], off offset:256
	s_nop 1
	v_lshlrev_b64 v[66:67], 5, v[74:75]
	v_lshl_add_u64 v[70:71], s[12:13], 0, v[66:67]
	s_waitcnt vmcnt(14)
	v_mov_b64_e32 v[66:67], v[184:185]
	v_mov_b64_e32 v[68:69], v[186:187]
	v_mov_b64_e32 v[70:71], v[188:189]
	v_mov_b64_e32 v[72:73], v[190:191]
	v_mov_b32_e32 v76, v66
	v_mov_b32_e32 v77, v70
	v_mov_b32_e32 v70, v67
	v_pk_add_f32 v[66:67], v[76:77], v[70:71]
	v_mov_b32_e32 v70, v68
	v_mov_b32_e32 v71, v72
	v_mov_b32_e32 v72, v69
	v_pk_add_f32 v[68:69], v[70:71], v[72:73]
	s_nop 0
	v_pk_add_f32 v[66:67], v[66:67], v[68:69]
	s_nop 0
	v_add_f32_e32 v66, 0, v66
	v_add_f32_e32 v66, v66, v67
	v_fmamk_f32 v66, v66, 0x3b800000, v241
	v_rsq_f32_e32 v66, v66
	s_nop 0
	v_pk_mul_f32 v[52:53], v[52:53], v[66:67] op_sel_hi:[1,0]
	v_pk_mul_f32 v[50:51], v[50:51], v[66:67] op_sel_hi:[1,0]
	v_pk_mul_f32 v[54:55], v[54:55], v[66:67] op_sel_hi:[1,0]
	v_cvt_pk_bf16_f32 v50, v50, v51
	v_cvt_pk_bf16_f32 v51, v52, v53
	v_pk_mul_f32 v[56:57], v[56:57], v[66:67] op_sel_hi:[1,0]
	v_cvt_pk_bf16_f32 v52, v54, v55
	v_lshlrev_b64 v[54:55], 11, v[74:75]
	v_lshl_add_u64 v[54:55], s[10:11], 0, v[54:55]
	v_cvt_pk_bf16_f32 v53, v56, v57
	v_lshl_add_u64 v[54:55], v[54:55], 0, v[114:115]
	global_store_dwordx4 v[54:55], v[50:53], off
	v_pk_mul_f32 v[56:57], v[64:65], v[66:67] op_sel_hi:[1,0]
	s_nop 0
	v_pk_mul_f32 v[52:53], v[60:61], v[66:67] op_sel_hi:[1,0]
	v_pk_mul_f32 v[50:51], v[58:59], v[66:67] op_sel_hi:[1,0]
	v_pk_mul_f32 v[58:59], v[62:63], v[66:67] op_sel_hi:[1,0]
	v_cvt_pk_bf16_f32 v50, v50, v51
	v_cvt_pk_bf16_f32 v51, v52, v53
	s_nop 0
	v_cvt_pk_bf16_f32 v52, v58, v59
	v_add_u32_e32 v58, 0x90, v136
	v_ashrrev_i32_e32 v59, 31, v58
	v_cvt_pk_bf16_f32 v53, v56, v57
	global_store_dwordx4 v[54:55], v[50:53], off offset:256
	s_nop 1
	v_lshlrev_b64 v[50:51], 5, v[58:59]
	v_lshl_add_u64 v[54:55], s[12:13], 0, v[50:51]
	s_waitcnt vmcnt(14)
; #define GAS __attribute__((address_space(1)))
; __device__ __forceinline__ unsigned cvtpk(float lo, float hi) { unsigned r; asm volatile("v_cvt_pk_bf16_f32 %0, %1, %2" : "=v"(r) : "v"(lo), "v"(hi)); return r; }
;     __device__ __forceinline__ void operator()(const f32x4 (&acc)[2][2][4][2], const pg8::Unit& u, int wr, int wc, int fr, int fq, const LAS float* scr) const {
;     ...
;             for (int m = 0; m < 4; ++m) { const int row = row0 + ai * 128 + m * 16; const float* rp = part + (size_t)row * NP; float q = 0.f;
; #pragma unroll
;                 for (int j = 0; j < NP / 4; ++j) { const f32x4 t = *(const GAS f32x4*)(rp + 4 * j); q += (t.x + t.y) + (t.z + t.w); }
;                 const float sc = __builtin_amdgcn_rsqf(q * inv_n + EPSN);
; #pragma unroll
;                 for (int bj = 0; bj < 2; ++bj) { const int c0 = u.pn * 256 + bj * 128 + wc * 32, col0 = c0 + 8 * fq;
;                     f32x4 v0 = acc[ai][bj][m][0] * sc, v1 = acc[ai][bj][m][1] * sc;
;                     if (ROPE && ((c0 & ~63) % 192) == 128) { const int j0 = ((c0 & 32) ? 16 : 0) + 4 * fq;
;                         const f32x4 c = *(const GAS f32x4*)(cosM + (size_t)row * 32 + j0), s = *(const GAS f32x4*)(sinM + (size_t)row * 32 + j0);
;                         const f32x4 a = v0 * c - v1 * s, b = v0 * s + v1 * c; v0 = a; v1 = b; }
;                     u32x4 w; w.x = cvtpk(v0[0], v0[1]); w.y = cvtpk(v0[2], v0[3]); w.z = cvtpk(v1[0], v1[1]); w.w = cvtpk(v1[2], v1[3]);
;                     *(GAS u32x4*)(O + (size_t)row * ldc + col0) = w; }
	v_mov_b64_e32 v[50:51], v[196:197]
	v_mov_b64_e32 v[52:53], v[198:199]
	v_mov_b64_e32 v[54:55], v[200:201]
	v_mov_b64_e32 v[56:57], v[202:203]
	v_mov_b32_e32 v60, v50
	v_mov_b32_e32 v61, v54
	v_mov_b32_e32 v54, v51
	v_pk_add_f32 v[50:51], v[60:61], v[54:55]
	v_mov_b32_e32 v54, v52
	v_mov_b32_e32 v55, v56
	v_mov_b32_e32 v56, v53
	v_pk_add_f32 v[52:53], v[54:55], v[56:57]
	s_nop 0
	v_pk_add_f32 v[50:51], v[50:51], v[52:53]
	s_nop 0
	v_add_f32_e32 v50, 0, v50
	v_add_f32_e32 v50, v50, v51
	v_fmamk_f32 v50, v50, 0x3b800000, v241
	v_rsq_f32_e32 v50, v50
	s_nop 0
	v_pk_mul_f32 v[36:37], v[36:37], v[50:51] op_sel_hi:[1,0]
	v_pk_mul_f32 v[34:35], v[34:35], v[50:51] op_sel_hi:[1,0]
	v_pk_mul_f32 v[38:39], v[38:39], v[50:51] op_sel_hi:[1,0]
	v_cvt_pk_bf16_f32 v34, v34, v35
	v_cvt_pk_bf16_f32 v35, v36, v37
	v_pk_mul_f32 v[40:41], v[40:41], v[50:51] op_sel_hi:[1,0]
	v_cvt_pk_bf16_f32 v36, v38, v39
	v_lshlrev_b64 v[38:39], 11, v[58:59]
	v_lshl_add_u64 v[38:39], s[10:11], 0, v[38:39]
	v_cvt_pk_bf16_f32 v37, v40, v41
	v_lshl_add_u64 v[38:39], v[38:39], 0, v[114:115]
	global_store_dwordx4 v[38:39], v[34:37], off
	v_pk_mul_f32 v[40:41], v[48:49], v[50:51] op_sel_hi:[1,0]
	s_nop 0
	v_pk_mul_f32 v[36:37], v[44:45], v[50:51] op_sel_hi:[1,0]
	v_pk_mul_f32 v[34:35], v[42:43], v[50:51] op_sel_hi:[1,0]
	v_pk_mul_f32 v[42:43], v[46:47], v[50:51] op_sel_hi:[1,0]
	v_cvt_pk_bf16_f32 v34, v34, v35
	v_cvt_pk_bf16_f32 v35, v36, v37
	s_nop 0
	v_cvt_pk_bf16_f32 v36, v42, v43
	v_add_u32_e32 v42, 0xa0, v136
	v_ashrrev_i32_e32 v43, 31, v42
	v_cvt_pk_bf16_f32 v37, v40, v41
	global_store_dwordx4 v[38:39], v[34:37], off offset:256
	s_nop 1
	v_lshlrev_b64 v[34:35], 5, v[42:43]
	v_lshl_add_u64 v[38:39], s[12:13], 0, v[34:35]
	s_waitcnt vmcnt(14)
	v_mov_b64_e32 v[34:35], v[204:205]
	v_mov_b64_e32 v[36:37], v[206:207]
	v_mov_b64_e32 v[38:39], v[208:209]
	v_mov_b64_e32 v[40:41], v[210:211]
	v_mov_b32_e32 v44, v34
	v_mov_b32_e32 v45, v38
	v_mov_b32_e32 v38, v35
	v_pk_add_f32 v[34:35], v[44:45], v[38:39]
	v_mov_b32_e32 v38, v36
	v_mov_b32_e32 v39, v40
	v_mov_b32_e32 v40, v37
	v_pk_add_f32 v[36:37], v[38:39], v[40:41]
	s_nop 0
	v_pk_add_f32 v[34:35], v[34:35], v[36:37]
	s_nop 0
	v_add_f32_e32 v34, 0, v34
	v_add_f32_e32 v34, v34, v35
	v_fmamk_f32 v34, v34, 0x3b800000, v241
	v_rsq_f32_e32 v34, v34
	s_nop 0
	v_pk_mul_f32 v[20:21], v[20:21], v[34:35] op_sel_hi:[1,0]
	v_pk_mul_f32 v[18:19], v[18:19], v[34:35] op_sel_hi:[1,0]
	v_pk_mul_f32 v[22:23], v[22:23], v[34:35] op_sel_hi:[1,0]
	v_cvt_pk_bf16_f32 v18, v18, v19
	v_cvt_pk_bf16_f32 v19, v20, v21
	v_pk_mul_f32 v[24:25], v[24:25], v[34:35] op_sel_hi:[1,0]
	v_cvt_pk_bf16_f32 v20, v22, v23
	v_lshlrev_b64 v[22:23], 11, v[42:43]
	v_lshl_add_u64 v[22:23], s[10:11], 0, v[22:23]
	v_cvt_pk_bf16_f32 v21, v24, v25
	v_lshl_add_u64 v[22:23], v[22:23], 0, v[114:115]
	global_store_dwordx4 v[22:23], v[18:21], off
	v_pk_mul_f32 v[24:25], v[32:33], v[34:35] op_sel_hi:[1,0]
	s_nop 0
	v_pk_mul_f32 v[20:21], v[28:29], v[34:35] op_sel_hi:[1,0]
	v_pk_mul_f32 v[18:19], v[26:27], v[34:35] op_sel_hi:[1,0]
	v_pk_mul_f32 v[26:27], v[30:31], v[34:35] op_sel_hi:[1,0]
	v_cvt_pk_bf16_f32 v18, v18, v19
	v_cvt_pk_bf16_f32 v19, v20, v21
	s_nop 0
	v_cvt_pk_bf16_f32 v20, v26, v27
	v_add_u32_e32 v26, 0xb0, v136
	v_ashrrev_i32_e32 v27, 31, v26
	v_cvt_pk_bf16_f32 v21, v24, v25
	global_store_dwordx4 v[22:23], v[18:21], off offset:256
	s_nop 1
	v_lshlrev_b64 v[18:19], 5, v[26:27]
	v_lshl_add_u64 v[22:23], s[12:13], 0, v[18:19]
	s_waitcnt vmcnt(14)
	v_mov_b64_e32 v[18:19], v[212:213]
	v_mov_b64_e32 v[20:21], v[214:215]
	v_mov_b64_e32 v[22:23], v[216:217]
	v_mov_b64_e32 v[24:25], v[218:219]
	v_mov_b32_e32 v28, v18
	v_mov_b32_e32 v29, v22
	v_mov_b32_e32 v22, v19
	v_pk_add_f32 v[18:19], v[28:29], v[22:23]
	v_mov_b32_e32 v22, v20
	v_mov_b32_e32 v23, v24
	v_mov_b32_e32 v24, v21
	v_pk_add_f32 v[20:21], v[22:23], v[24:25]
	s_nop 0
	v_pk_add_f32 v[18:19], v[18:19], v[20:21]
	s_nop 0
	v_add_f32_e32 v18, 0, v18
	v_add_f32_e32 v18, v18, v19
	v_fmamk_f32 v18, v18, 0x3b800000, v241
	v_rsq_f32_e32 v18, v18
	s_nop 0
	v_pk_mul_f32 v[12:13], v[12:13], v[18:19] op_sel_hi:[1,0]
	v_pk_mul_f32 v[10:11], v[10:11], v[18:19] op_sel_hi:[1,0]
	v_pk_mul_f32 v[14:15], v[14:15], v[18:19] op_sel_hi:[1,0]
	v_cvt_pk_bf16_f32 v10, v10, v11
	v_cvt_pk_bf16_f32 v11, v12, v13
	v_pk_mul_f32 v[16:17], v[16:17], v[18:19] op_sel_hi:[1,0]
	v_cvt_pk_bf16_f32 v12, v14, v15
	v_lshlrev_b64 v[14:15], 11, v[26:27]
	v_lshl_add_u64 v[14:15], s[10:11], 0, v[14:15]
	v_lshl_add_u64 v[14:15], v[14:15], 0, v[114:115]
	v_cvt_pk_bf16_f32 v13, v16, v17
	global_store_dwordx4 v[14:15], v[10:13], off
	v_pk_mul_f32 v[8:9], v[8:9], v[18:19] op_sel_hi:[1,0]
	v_pk_mul_f32 v[6:7], v[6:7], v[18:19] op_sel_hi:[1,0]
	v_pk_mul_f32 v[10:11], v[4:5], v[18:19] op_sel_hi:[1,0]
	v_pk_mul_f32 v[4:5], v[2:3], v[18:19] op_sel_hi:[1,0]
	v_cvt_pk_bf16_f32 v2, v6, v7
	v_cvt_pk_bf16_f32 v3, v8, v9
	s_nop 0
	v_cvt_pk_bf16_f32 v4, v4, v5
	v_cvt_pk_bf16_f32 v5, v10, v11
	global_store_dwordx4 v[14:15], v[2:5], off offset:256
	s_cbranch_vccnz .LBB0_796
	s_andn2_b64 vcc, exec, s[4:5]
	s_cbranch_vccnz .LBB0_795
	s_barrier
	s_branch .LBB0_795
